# nt cache hint on QKV and MLP-up epilogue stores (write-once streams)
# speedup vs baseline: 1.0074x; 1.0074x over previous
.LBB0_220:
	s_xor_b64 s[30:31], s[4:5], -1
	s_lshl_b32 s4, s90, 8
	s_ashr_i32 s5, s4, 31
	s_lshl_b64 s[4:5], s[4:5], 1
	s_add_u32 s4, s28, s4
	s_addc_u32 s5, s29, s5
	v_lshlrev_b32_e32 v160, 1, v174
	v_lshl_add_u64 v[144:145], s[4:5], 0, v[160:161]
	s_waitcnt lgkmcnt(3)
	v_mul_lo_u32 v148, s27, v180
	s_waitcnt lgkmcnt(2)
	v_mul_lo_u32 v149, s26, v181
	v_mad_u64_u32 v[146:147], s[4:5], s26, v180, 0
	v_add3_u32 v147, v147, v149, v148
	v_lshl_add_u64 v[150:151], v[146:147], 1, v[144:145]
	v_cvt_pk_bf16_f32 v146, v192, v193
	v_cvt_pk_bf16_f32 v147, v190, v191
	v_cvt_pk_bf16_f32 v148, v188, v189
	v_cvt_pk_bf16_f32 v149, v186, v187
	global_store_dwordx4 v[150:151], v[146:149], off nt
	s_andn2_b64 vcc, exec, s[30:31]
	s_nop 0
	v_cvt_pk_bf16_f32 v146, v184, v185
	v_cvt_pk_bf16_f32 v147, v182, v183
	v_cvt_pk_bf16_f32 v148, v158, v159
	v_cvt_pk_bf16_f32 v149, v156, v157
	global_store_dwordx4 v[150:151], v[146:149], off offset:64 nt
	s_nop 1
	v_add_u32_e32 v146, s21, v209
	v_ashrrev_i32_e32 v147, 31, v146
	v_lshl_add_u64 v[148:149], v[146:147], 2, s[42:43]
	global_load_dword v148, v[148:149], off
	s_waitcnt vmcnt(0)
	v_fmamk_f32 v148, v148, 0x3a800000, v204
	v_rsq_f32_e32 v160, v148
	v_cndmask_b32_e64 v148, 0, 1, s[30:31]
	v_cmp_ne_u32_e64 s[4:5], 1, v148
	v_pk_fma_f32 v[156:157], v[142:143], v[160:161], v[78:79] op_sel_hi:[1,0,1]
	v_pk_fma_f32 v[158:159], v[140:141], v[160:161], v[76:77] op_sel_hi:[1,0,1]
	v_pk_fma_f32 v[152:153], v[138:139], v[160:161], v[74:75] op_sel_hi:[1,0,1]
	v_pk_fma_f32 v[154:155], v[136:137], v[160:161], v[72:73] op_sel_hi:[1,0,1]
	v_pk_fma_f32 v[148:149], v[134:135], v[160:161], v[70:71] op_sel_hi:[1,0,1]
	v_pk_fma_f32 v[150:151], v[132:133], v[160:161], v[68:69] op_sel_hi:[1,0,1]
	v_pk_fma_f32 v[140:141], v[130:131], v[160:161], v[66:67] op_sel_hi:[1,0,1]
	v_pk_fma_f32 v[142:143], v[128:129], v[160:161], v[64:65] op_sel_hi:[1,0,1]
	s_cbranch_vccnz .LBB0_234
	v_pk_mul_f32 v[128:129], v[156:157], v[156:157]
	v_pk_mul_f32 v[130:131], v[158:159], v[158:159]
	v_cmp_lt_i32_e32 vcc, 0, v175
	v_pk_mov_b32 v[132:133], v[130:131], v[128:129] op_sel:[1,0]
	v_mov_b32_e32 v131, v129
	v_pk_add_f32 v[128:129], v[132:133], v[130:131]
	v_pk_mul_f32 v[130:131], v[152:153], v[152:153]
	v_pk_add_f32 v[128:129], v[128:129], v[128:129] op_sel_hi:[0,1]
	v_pk_mul_f32 v[132:133], v[154:155], v[154:155]
	v_mul_f32_e32 v128, v150, v150
	v_pk_mov_b32 v[134:135], v[132:133], v[130:131] op_sel:[1,0]
	v_mov_b32_e32 v133, v131
	v_pk_add_f32 v[130:131], v[134:135], v[132:133]
	v_pk_fma_f32 v[132:133], v[150:151], v[150:151], v[128:129] op_sel_hi:[1,1,0]
	v_mul_f32_e32 v128, v148, v148
	v_pk_add_f32 v[130:131], v[130:131], v[130:131] op_sel_hi:[0,1]
	v_pk_fma_f32 v[134:135], v[148:149], v[148:149], v[128:129] op_sel_hi:[1,1,0]
	v_mul_f32_e32 v132, v142, v142
	v_mul_f32_e32 v134, v143, v143
	v_mul_f32_e32 v128, v140, v140
	v_mul_f32_e32 v130, v141, v141
	v_pk_add_f32 v[132:133], v[132:133], v[134:135]
	v_pk_add_f32 v[128:129], v[128:129], v[130:131]
	v_pk_mul_f32 v[130:131], v[60:61], v[158:159]
	v_pk_add_f32 v[128:129], v[132:133], v[128:129]
	s_nop 0
	v_add_f32_e32 v128, v128, v129
	ds_swizzle_b32 v129, v128 offset:swizzle(SWAP,16)
	s_waitcnt lgkmcnt(0)
	v_add_f32_e32 v128, v128, v129
	v_mov_b32_e32 v129, v128
	s_nop 1
	v_permlane32_swap_b32_e32 v128, v129
	v_add_f32_e32 v128, v128, v129
	v_fmamk_f32 v128, v128, 0x3c800000, v204
	v_rsq_f32_e32 v128, v128
	s_nop 0
	v_mul_f32_e32 v182, s19, v128
	v_mov_b32_e32 v183, v182
	v_pk_mul_f32 v[158:159], v[130:131], v[182:183] op_sel_hi:[1,0]
	v_lshlrev_b64 v[130:131], 5, v[146:147]
	v_lshl_add_u64 v[186:187], s[50:51], 0, v[130:131]
	v_lshl_add_u64 v[188:189], s[60:61], 0, v[130:131]
	global_load_dwordx4 v[136:139], v[186:187], off
	global_load_dwordx4 v[132:135], v[188:189], off
	v_pk_mul_f32 v[128:129], v[62:63], v[156:157]
	v_mov_b32_e32 v184, v182
	v_pk_mul_f32 v[156:157], v[128:129], v[182:183] op_sel_hi:[1,0]
	ds_swizzle_b32 v128, v158 offset:swizzle(SWAP,16)
	ds_swizzle_b32 v129, v159 offset:swizzle(SWAP,16)
	ds_swizzle_b32 v190, v156 offset:swizzle(SWAP,16)
	ds_swizzle_b32 v191, v157 offset:swizzle(SWAP,16)
	v_mov_b32_e32 v185, v182
	s_and_saveexec_b64 s[28:29], vcc
	s_xor_b64 s[28:29], exec, s[28:29]
	s_cbranch_execz .LBB0_225
	v_cmp_eq_u32_e32 vcc, 1, v175
	s_and_saveexec_b64 s[30:31], vcc
	s_cbranch_execz .LBB0_224
	s_waitcnt vmcnt(1)
	v_pk_mul_f32 v[130:131], v[138:139], v[156:157]
	v_pk_mul_f32 v[136:137], v[136:137], v[158:159]
	s_waitcnt vmcnt(0) lgkmcnt(0)
	v_pk_fma_f32 v[156:157], v[134:135], v[190:191], v[130:131]
	v_pk_fma_f32 v[158:159], v[132:133], v[128:129], v[136:137]

.LBB0_234:
	v_mul_lo_u32 v130, s27, v146
	v_mul_lo_u32 v131, s26, v147
	v_mad_u64_u32 v[128:129], s[28:29], s26, v146, 0
	v_add3_u32 v129, v129, v131, v130
	s_waitcnt lgkmcnt(2)
	v_lshl_add_u64 v[132:133], v[128:129], 1, v[144:145]
	v_cvt_pk_bf16_f32 v128, v158, v159
	v_cvt_pk_bf16_f32 v129, v156, v157
	v_cvt_pk_bf16_f32 v130, v154, v155
	v_cvt_pk_bf16_f32 v131, v152, v153
	global_store_dwordx4 v[132:133], v[128:131], off nt
	s_and_b64 vcc, exec, s[4:5]
	s_nop 0
	v_cvt_pk_bf16_f32 v128, v150, v151
	v_cvt_pk_bf16_f32 v129, v148, v149
	v_cvt_pk_bf16_f32 v130, v142, v143
	v_cvt_pk_bf16_f32 v131, v140, v141
	global_store_dwordx4 v[132:133], v[128:131], off offset:64 nt
	s_nop 1
	v_add_u32_e32 v128, s21, v210
	v_ashrrev_i32_e32 v129, 31, v128
	v_lshl_add_u64 v[130:131], v[128:129], 2, s[42:43]
	global_load_dword v130, v[130:131], off
	s_waitcnt vmcnt(0)
	v_fmamk_f32 v130, v130, 0x3a800000, v204
	v_rsq_f32_e32 v142, v130
	s_nop 0
	v_pk_fma_f32 v[138:139], v[126:127], v[142:143], v[78:79] op_sel_hi:[1,0,1]
	v_pk_fma_f32 v[140:141], v[124:125], v[142:143], v[76:77] op_sel_hi:[1,0,1]
	v_pk_fma_f32 v[134:135], v[122:123], v[142:143], v[74:75] op_sel_hi:[1,0,1]
	v_pk_fma_f32 v[136:137], v[120:121], v[142:143], v[72:73] op_sel_hi:[1,0,1]
	v_pk_fma_f32 v[130:131], v[118:119], v[142:143], v[70:71] op_sel_hi:[1,0,1]
	v_pk_fma_f32 v[132:133], v[116:117], v[142:143], v[68:69] op_sel_hi:[1,0,1]
	v_pk_fma_f32 v[124:125], v[114:115], v[142:143], v[66:67] op_sel_hi:[1,0,1]
	v_pk_fma_f32 v[126:127], v[112:113], v[142:143], v[64:65] op_sel_hi:[1,0,1]
	s_cbranch_vccnz .LBB0_248
	v_pk_mul_f32 v[112:113], v[138:139], v[138:139]
	v_pk_mul_f32 v[114:115], v[140:141], v[140:141]
	v_cmp_lt_i32_e32 vcc, 0, v175
	v_pk_mov_b32 v[116:117], v[114:115], v[112:113] op_sel:[1,0]
	v_mov_b32_e32 v115, v113
	v_pk_add_f32 v[112:113], v[116:117], v[114:115]
	v_pk_mul_f32 v[114:115], v[134:135], v[134:135]
	v_pk_add_f32 v[112:113], v[112:113], v[112:113] op_sel_hi:[0,1]
	v_pk_mul_f32 v[116:117], v[136:137], v[136:137]
	v_mul_f32_e32 v112, v132, v132
	v_pk_mov_b32 v[118:119], v[116:117], v[114:115] op_sel:[1,0]
	v_mov_b32_e32 v117, v115
	v_pk_add_f32 v[114:115], v[118:119], v[116:117]
	v_pk_fma_f32 v[116:117], v[132:133], v[132:133], v[112:113] op_sel_hi:[1,1,0]
	v_mul_f32_e32 v112, v130, v130
	v_pk_add_f32 v[114:115], v[114:115], v[114:115] op_sel_hi:[0,1]
	v_pk_fma_f32 v[118:119], v[130:131], v[130:131], v[112:113] op_sel_hi:[1,1,0]
	v_mul_f32_e32 v116, v126, v126
	v_mul_f32_e32 v118, v127, v127
	v_mul_f32_e32 v112, v124, v124
	v_mul_f32_e32 v114, v125, v125
	v_pk_add_f32 v[116:117], v[116:117], v[118:119]
	v_pk_add_f32 v[112:113], v[112:113], v[114:115]
	v_pk_mul_f32 v[114:115], v[60:61], v[140:141]
	v_pk_add_f32 v[112:113], v[116:117], v[112:113]
	s_nop 0
	v_add_f32_e32 v112, v112, v113
	ds_swizzle_b32 v113, v112 offset:swizzle(SWAP,16)
	s_waitcnt lgkmcnt(0)
	v_add_f32_e32 v112, v112, v113
	v_mov_b32_e32 v113, v112
	s_nop 1
	v_permlane32_swap_b32_e32 v112, v113
	v_add_f32_e32 v112, v112, v113
	v_fmamk_f32 v112, v112, 0x3c800000, v204
	v_rsq_f32_e32 v112, v112
	s_nop 0
	v_mul_f32_e32 v142, s19, v112
	v_mov_b32_e32 v143, v142
	v_pk_mul_f32 v[140:141], v[114:115], v[142:143] op_sel_hi:[1,0]
	v_lshlrev_b64 v[114:115], 5, v[128:129]
	v_lshl_add_u64 v[148:149], s[50:51], 0, v[114:115]
	v_lshl_add_u64 v[150:151], s[60:61], 0, v[114:115]
	global_load_dwordx4 v[120:123], v[148:149], off
	global_load_dwordx4 v[116:119], v[150:151], off
	v_pk_mul_f32 v[112:113], v[62:63], v[138:139]
	v_mov_b32_e32 v146, v142
	v_pk_mul_f32 v[138:139], v[112:113], v[142:143] op_sel_hi:[1,0]
	ds_swizzle_b32 v112, v140 offset:swizzle(SWAP,16)
	ds_swizzle_b32 v113, v141 offset:swizzle(SWAP,16)
	ds_swizzle_b32 v152, v138 offset:swizzle(SWAP,16)
	ds_swizzle_b32 v153, v139 offset:swizzle(SWAP,16)
	v_mov_b32_e32 v147, v142
	s_and_saveexec_b64 s[28:29], vcc
	s_xor_b64 s[28:29], exec, s[28:29]
	s_cbranch_execz .LBB0_239
	v_cmp_eq_u32_e32 vcc, 1, v175
	s_and_saveexec_b64 s[30:31], vcc
	s_cbranch_execz .LBB0_238
	s_waitcnt vmcnt(1)
	v_pk_mul_f32 v[114:115], v[122:123], v[138:139]
	v_pk_mul_f32 v[120:121], v[120:121], v[140:141]
	s_waitcnt vmcnt(0) lgkmcnt(0)
	v_pk_fma_f32 v[138:139], v[118:119], v[152:153], v[114:115]
	v_pk_fma_f32 v[140:141], v[116:117], v[112:113], v[120:121]

.LBB0_248:
	v_mul_lo_u32 v114, s27, v128
	v_mul_lo_u32 v115, s26, v129
	v_mad_u64_u32 v[112:113], s[28:29], s26, v128, 0
	v_add3_u32 v113, v113, v115, v114
	s_waitcnt lgkmcnt(2)
	v_lshl_add_u64 v[116:117], v[112:113], 1, v[144:145]
	v_cvt_pk_bf16_f32 v112, v140, v141
	v_cvt_pk_bf16_f32 v113, v138, v139
	v_cvt_pk_bf16_f32 v114, v136, v137
	v_cvt_pk_bf16_f32 v115, v134, v135
	global_store_dwordx4 v[116:117], v[112:115], off nt
	s_and_b64 vcc, exec, s[4:5]
	s_nop 0
	v_cvt_pk_bf16_f32 v112, v132, v133
	v_cvt_pk_bf16_f32 v113, v130, v131
	v_cvt_pk_bf16_f32 v114, v126, v127
	v_cvt_pk_bf16_f32 v115, v124, v125
	global_store_dwordx4 v[116:117], v[112:115], off offset:64 nt
	s_nop 1
	v_add_u32_e32 v112, s21, v211
	v_ashrrev_i32_e32 v113, 31, v112
	v_lshl_add_u64 v[114:115], v[112:113], 2, s[42:43]
	global_load_dword v114, v[114:115], off
	s_waitcnt vmcnt(0)
	v_fmamk_f32 v114, v114, 0x3a800000, v204
	v_rsq_f32_e32 v126, v114
	s_nop 0
	v_pk_fma_f32 v[122:123], v[110:111], v[126:127], v[78:79] op_sel_hi:[1,0,1]
	v_pk_fma_f32 v[124:125], v[108:109], v[126:127], v[76:77] op_sel_hi:[1,0,1]
	v_pk_fma_f32 v[118:119], v[106:107], v[126:127], v[74:75] op_sel_hi:[1,0,1]
	v_pk_fma_f32 v[120:121], v[104:105], v[126:127], v[72:73] op_sel_hi:[1,0,1]
	v_pk_fma_f32 v[114:115], v[102:103], v[126:127], v[70:71] op_sel_hi:[1,0,1]
	v_pk_fma_f32 v[116:117], v[100:101], v[126:127], v[68:69] op_sel_hi:[1,0,1]
	v_pk_fma_f32 v[108:109], v[98:99], v[126:127], v[66:67] op_sel_hi:[1,0,1]
	v_pk_fma_f32 v[110:111], v[96:97], v[126:127], v[64:65] op_sel_hi:[1,0,1]
	s_cbranch_vccnz .LBB0_262
	v_pk_mul_f32 v[96:97], v[122:123], v[122:123]
	v_pk_mul_f32 v[98:99], v[124:125], v[124:125]
	v_cmp_lt_i32_e32 vcc, 0, v175
	v_pk_mov_b32 v[100:101], v[98:99], v[96:97] op_sel:[1,0]
	v_mov_b32_e32 v99, v97
	v_pk_add_f32 v[96:97], v[100:101], v[98:99]
	v_pk_mul_f32 v[98:99], v[118:119], v[118:119]
	v_pk_add_f32 v[96:97], v[96:97], v[96:97] op_sel_hi:[0,1]
	v_pk_mul_f32 v[100:101], v[120:121], v[120:121]
	v_mul_f32_e32 v96, v116, v116
	v_pk_mov_b32 v[102:103], v[100:101], v[98:99] op_sel:[1,0]
	v_mov_b32_e32 v101, v99
	v_pk_add_f32 v[98:99], v[102:103], v[100:101]
	v_pk_fma_f32 v[100:101], v[116:117], v[116:117], v[96:97] op_sel_hi:[1,1,0]
	v_mul_f32_e32 v96, v114, v114
	v_pk_add_f32 v[98:99], v[98:99], v[98:99] op_sel_hi:[0,1]
	v_pk_fma_f32 v[102:103], v[114:115], v[114:115], v[96:97] op_sel_hi:[1,1,0]
	v_mul_f32_e32 v100, v110, v110
	v_mul_f32_e32 v102, v111, v111
	v_mul_f32_e32 v96, v108, v108
	v_mul_f32_e32 v98, v109, v109
	v_pk_add_f32 v[100:101], v[100:101], v[102:103]
	v_pk_add_f32 v[96:97], v[96:97], v[98:99]
	v_pk_mul_f32 v[98:99], v[60:61], v[124:125]
	v_pk_add_f32 v[96:97], v[100:101], v[96:97]
	s_nop 0
	v_add_f32_e32 v96, v96, v97
	ds_swizzle_b32 v97, v96 offset:swizzle(SWAP,16)
	s_waitcnt lgkmcnt(0)
	v_add_f32_e32 v96, v96, v97
	v_mov_b32_e32 v97, v96
	s_nop 1
	v_permlane32_swap_b32_e32 v96, v97
	v_add_f32_e32 v96, v96, v97
	v_fmamk_f32 v96, v96, 0x3c800000, v204
	v_rsq_f32_e32 v96, v96
	s_nop 0
	v_mul_f32_e32 v126, s19, v96
	v_mov_b32_e32 v127, v126
	v_pk_mul_f32 v[124:125], v[98:99], v[126:127] op_sel_hi:[1,0]
	v_lshlrev_b64 v[98:99], 5, v[112:113]
	v_lshl_add_u64 v[130:131], s[50:51], 0, v[98:99]
	v_lshl_add_u64 v[132:133], s[60:61], 0, v[98:99]
	global_load_dwordx4 v[104:107], v[130:131], off
	global_load_dwordx4 v[100:103], v[132:133], off
	v_pk_mul_f32 v[96:97], v[62:63], v[122:123]
	v_mov_b32_e32 v128, v126
	v_pk_mul_f32 v[122:123], v[96:97], v[126:127] op_sel_hi:[1,0]
	ds_swizzle_b32 v96, v124 offset:swizzle(SWAP,16)
	ds_swizzle_b32 v97, v125 offset:swizzle(SWAP,16)
	ds_swizzle_b32 v134, v122 offset:swizzle(SWAP,16)
	ds_swizzle_b32 v135, v123 offset:swizzle(SWAP,16)
	v_mov_b32_e32 v129, v126
	s_and_saveexec_b64 s[28:29], vcc
	s_xor_b64 s[28:29], exec, s[28:29]
	s_cbranch_execz .LBB0_253
	v_cmp_eq_u32_e32 vcc, 1, v175
	s_and_saveexec_b64 s[30:31], vcc
	s_cbranch_execz .LBB0_252
	s_waitcnt vmcnt(1)
	v_pk_mul_f32 v[98:99], v[106:107], v[122:123]
	v_pk_mul_f32 v[104:105], v[104:105], v[124:125]
	s_waitcnt vmcnt(0) lgkmcnt(0)
	v_pk_fma_f32 v[122:123], v[102:103], v[134:135], v[98:99]
	v_pk_fma_f32 v[124:125], v[100:101], v[96:97], v[104:105]

.LBB0_262:
	v_mul_lo_u32 v98, s27, v112
	v_mul_lo_u32 v99, s26, v113
	v_mad_u64_u32 v[96:97], s[28:29], s26, v112, 0
	v_add3_u32 v97, v97, v99, v98
	s_waitcnt lgkmcnt(2)
	v_lshl_add_u64 v[100:101], v[96:97], 1, v[144:145]
	v_cvt_pk_bf16_f32 v96, v124, v125
	v_cvt_pk_bf16_f32 v97, v122, v123
	v_cvt_pk_bf16_f32 v98, v120, v121
	v_cvt_pk_bf16_f32 v99, v118, v119
	global_store_dwordx4 v[100:101], v[96:99], off nt
	s_and_b64 vcc, exec, s[4:5]
	s_nop 0
	v_cvt_pk_bf16_f32 v96, v116, v117
	v_cvt_pk_bf16_f32 v97, v114, v115
	v_cvt_pk_bf16_f32 v98, v110, v111
	v_cvt_pk_bf16_f32 v99, v108, v109
	global_store_dwordx4 v[100:101], v[96:99], off offset:64 nt
	s_nop 1
	v_add_u32_e32 v96, 0x80, v180
	v_ashrrev_i32_e32 v97, 31, v96
	v_lshl_add_u64 v[98:99], v[96:97], 2, s[42:43]
	global_load_dword v98, v[98:99], off
	s_waitcnt vmcnt(0)
	v_fmamk_f32 v98, v98, 0x3a800000, v204
	v_rsq_f32_e32 v110, v98
	s_nop 0
	v_pk_fma_f32 v[106:107], v[94:95], v[110:111], v[78:79] op_sel_hi:[1,0,1]
	v_pk_fma_f32 v[108:109], v[92:93], v[110:111], v[76:77] op_sel_hi:[1,0,1]
	v_pk_fma_f32 v[102:103], v[90:91], v[110:111], v[74:75] op_sel_hi:[1,0,1]
	v_pk_fma_f32 v[104:105], v[88:89], v[110:111], v[72:73] op_sel_hi:[1,0,1]
	v_pk_fma_f32 v[98:99], v[86:87], v[110:111], v[70:71] op_sel_hi:[1,0,1]
	v_pk_fma_f32 v[100:101], v[84:85], v[110:111], v[68:69] op_sel_hi:[1,0,1]
	v_pk_fma_f32 v[92:93], v[82:83], v[110:111], v[66:67] op_sel_hi:[1,0,1]
	v_pk_fma_f32 v[94:95], v[80:81], v[110:111], v[64:65] op_sel_hi:[1,0,1]
	s_cbranch_vccnz .LBB0_276
	v_pk_mul_f32 v[80:81], v[106:107], v[106:107]
	v_pk_mul_f32 v[82:83], v[108:109], v[108:109]
	v_cmp_lt_i32_e32 vcc, 0, v175
	v_pk_mov_b32 v[84:85], v[82:83], v[80:81] op_sel:[1,0]
	v_mov_b32_e32 v83, v81
	v_pk_add_f32 v[80:81], v[84:85], v[82:83]
	v_pk_mul_f32 v[82:83], v[102:103], v[102:103]
	v_pk_add_f32 v[80:81], v[80:81], v[80:81] op_sel_hi:[0,1]
	v_pk_mul_f32 v[84:85], v[104:105], v[104:105]
	v_mul_f32_e32 v80, v100, v100
	v_pk_mov_b32 v[86:87], v[84:85], v[82:83] op_sel:[1,0]
	v_mov_b32_e32 v85, v83
	v_pk_add_f32 v[82:83], v[86:87], v[84:85]
	v_pk_fma_f32 v[84:85], v[100:101], v[100:101], v[80:81] op_sel_hi:[1,1,0]
	v_mul_f32_e32 v80, v98, v98
	v_pk_add_f32 v[82:83], v[82:83], v[82:83] op_sel_hi:[0,1]
	v_pk_fma_f32 v[86:87], v[98:99], v[98:99], v[80:81] op_sel_hi:[1,1,0]
	v_mul_f32_e32 v84, v94, v94
	v_mul_f32_e32 v86, v95, v95
	v_mul_f32_e32 v80, v92, v92
	v_mul_f32_e32 v82, v93, v93
	v_pk_add_f32 v[84:85], v[84:85], v[86:87]
	v_pk_add_f32 v[80:81], v[80:81], v[82:83]
	v_pk_mul_f32 v[82:83], v[60:61], v[108:109]
	v_pk_add_f32 v[80:81], v[84:85], v[80:81]
	s_nop 0
	v_add_f32_e32 v80, v80, v81
	ds_swizzle_b32 v81, v80 offset:swizzle(SWAP,16)
	s_waitcnt lgkmcnt(0)
	v_add_f32_e32 v80, v80, v81
	v_mov_b32_e32 v81, v80
	s_nop 1
	v_permlane32_swap_b32_e32 v80, v81
	v_add_f32_e32 v80, v80, v81
	v_fmamk_f32 v80, v80, 0x3c800000, v204
	v_rsq_f32_e32 v80, v80
	s_nop 0
	v_mul_f32_e32 v110, s19, v80
	v_mov_b32_e32 v111, v110
	v_pk_mul_f32 v[108:109], v[82:83], v[110:111] op_sel_hi:[1,0]
	v_lshlrev_b64 v[82:83], 5, v[96:97]
	v_lshl_add_u64 v[114:115], s[50:51], 0, v[82:83]
	v_lshl_add_u64 v[116:117], s[60:61], 0, v[82:83]
	global_load_dwordx4 v[88:91], v[114:115], off
	global_load_dwordx4 v[84:87], v[116:117], off
	v_pk_mul_f32 v[80:81], v[62:63], v[106:107]
	v_mov_b32_e32 v112, v110
	v_pk_mul_f32 v[106:107], v[80:81], v[110:111] op_sel_hi:[1,0]
	ds_swizzle_b32 v80, v108 offset:swizzle(SWAP,16)
	ds_swizzle_b32 v81, v109 offset:swizzle(SWAP,16)
	ds_swizzle_b32 v118, v106 offset:swizzle(SWAP,16)
	ds_swizzle_b32 v119, v107 offset:swizzle(SWAP,16)
	v_mov_b32_e32 v113, v110
	s_and_saveexec_b64 s[28:29], vcc
	s_xor_b64 s[28:29], exec, s[28:29]
	s_cbranch_execz .LBB0_267
	v_cmp_eq_u32_e32 vcc, 1, v175
	s_and_saveexec_b64 s[30:31], vcc
	s_cbranch_execz .LBB0_266
	s_waitcnt vmcnt(1)
	v_pk_mul_f32 v[82:83], v[90:91], v[106:107]
	v_pk_mul_f32 v[88:89], v[88:89], v[108:109]
	s_waitcnt vmcnt(0) lgkmcnt(0)
	v_pk_fma_f32 v[106:107], v[86:87], v[118:119], v[82:83]
	v_pk_fma_f32 v[108:109], v[84:85], v[80:81], v[88:89]

.LBB0_276:
	v_mul_lo_u32 v82, s27, v96
	v_mul_lo_u32 v83, s26, v97
	v_mad_u64_u32 v[80:81], s[28:29], s26, v96, 0
	v_add3_u32 v81, v81, v83, v82
	s_waitcnt lgkmcnt(2)
	v_lshl_add_u64 v[84:85], v[80:81], 1, v[144:145]
	v_cvt_pk_bf16_f32 v80, v108, v109
	v_cvt_pk_bf16_f32 v81, v106, v107
	v_cvt_pk_bf16_f32 v82, v104, v105
	v_cvt_pk_bf16_f32 v83, v102, v103
	global_store_dwordx4 v[84:85], v[80:83], off nt
	s_and_b64 vcc, exec, s[4:5]
	s_nop 0
	v_cvt_pk_bf16_f32 v80, v100, v101
	v_cvt_pk_bf16_f32 v81, v98, v99
	v_cvt_pk_bf16_f32 v82, v94, v95
	v_cvt_pk_bf16_f32 v83, v92, v93
	global_store_dwordx4 v[84:85], v[80:83], off offset:64 nt
	s_nop 1
	v_add_u32_e32 v80, 0x90, v180
	v_ashrrev_i32_e32 v81, 31, v80
	v_lshl_add_u64 v[82:83], v[80:81], 2, s[42:43]
	global_load_dword v82, v[82:83], off
	s_waitcnt vmcnt(0)
	v_fmamk_f32 v82, v82, 0x3a800000, v204
	v_rsq_f32_e32 v94, v82
	s_nop 0
	v_pk_fma_f32 v[90:91], v[54:55], v[94:95], v[78:79] op_sel_hi:[1,0,1]
	v_pk_fma_f32 v[92:93], v[52:53], v[94:95], v[76:77] op_sel_hi:[1,0,1]
	v_pk_fma_f32 v[86:87], v[50:51], v[94:95], v[74:75] op_sel_hi:[1,0,1]
	v_pk_fma_f32 v[88:89], v[48:49], v[94:95], v[72:73] op_sel_hi:[1,0,1]
	v_pk_fma_f32 v[82:83], v[46:47], v[94:95], v[70:71] op_sel_hi:[1,0,1]
	v_pk_fma_f32 v[84:85], v[44:45], v[94:95], v[68:69] op_sel_hi:[1,0,1]
	v_pk_fma_f32 v[52:53], v[42:43], v[94:95], v[66:67] op_sel_hi:[1,0,1]
	v_pk_fma_f32 v[54:55], v[40:41], v[94:95], v[64:65] op_sel_hi:[1,0,1]
	s_cbranch_vccnz .LBB0_290
	v_pk_mul_f32 v[40:41], v[90:91], v[90:91]
	v_pk_mul_f32 v[42:43], v[92:93], v[92:93]
	v_cmp_lt_i32_e32 vcc, 0, v175
	v_pk_mov_b32 v[44:45], v[42:43], v[40:41] op_sel:[1,0]
	v_mov_b32_e32 v43, v41
	v_pk_add_f32 v[40:41], v[44:45], v[42:43]
	v_pk_mul_f32 v[42:43], v[86:87], v[86:87]
	v_pk_add_f32 v[40:41], v[40:41], v[40:41] op_sel_hi:[0,1]
	v_pk_mul_f32 v[44:45], v[88:89], v[88:89]
	v_mul_f32_e32 v40, v84, v84
	v_pk_mov_b32 v[46:47], v[44:45], v[42:43] op_sel:[1,0]
	v_mov_b32_e32 v45, v43
	v_pk_add_f32 v[42:43], v[46:47], v[44:45]
	v_pk_fma_f32 v[44:45], v[84:85], v[84:85], v[40:41] op_sel_hi:[1,1,0]
	v_mul_f32_e32 v40, v82, v82
	v_pk_add_f32 v[42:43], v[42:43], v[42:43] op_sel_hi:[0,1]
	v_pk_fma_f32 v[46:47], v[82:83], v[82:83], v[40:41] op_sel_hi:[1,1,0]
	v_mul_f32_e32 v44, v54, v54
	v_mul_f32_e32 v46, v55, v55
	v_mul_f32_e32 v40, v52, v52
	v_mul_f32_e32 v42, v53, v53
	v_pk_add_f32 v[44:45], v[44:45], v[46:47]
	v_pk_add_f32 v[40:41], v[40:41], v[42:43]
	v_pk_mul_f32 v[42:43], v[60:61], v[92:93]
	v_pk_add_f32 v[40:41], v[44:45], v[40:41]
	s_nop 0
	v_add_f32_e32 v40, v40, v41
	ds_swizzle_b32 v41, v40 offset:swizzle(SWAP,16)
	s_waitcnt lgkmcnt(0)
	v_add_f32_e32 v40, v40, v41
	v_mov_b32_e32 v41, v40
	s_nop 1
	v_permlane32_swap_b32_e32 v40, v41
	v_add_f32_e32 v40, v40, v41
	v_fmamk_f32 v40, v40, 0x3c800000, v204
	v_rsq_f32_e32 v40, v40
	s_nop 0
	v_mul_f32_e32 v94, s19, v40
	v_mov_b32_e32 v95, v94
	v_pk_mul_f32 v[92:93], v[42:43], v[94:95] op_sel_hi:[1,0]
	v_lshlrev_b64 v[42:43], 5, v[80:81]
	v_lshl_add_u64 v[98:99], s[50:51], 0, v[42:43]
	v_lshl_add_u64 v[100:101], s[60:61], 0, v[42:43]
	global_load_dwordx4 v[48:51], v[98:99], off
	global_load_dwordx4 v[44:47], v[100:101], off
	v_pk_mul_f32 v[40:41], v[62:63], v[90:91]
	v_mov_b32_e32 v96, v94
	v_pk_mul_f32 v[90:91], v[40:41], v[94:95] op_sel_hi:[1,0]
	ds_swizzle_b32 v40, v92 offset:swizzle(SWAP,16)
	ds_swizzle_b32 v41, v93 offset:swizzle(SWAP,16)
	ds_swizzle_b32 v102, v90 offset:swizzle(SWAP,16)
	ds_swizzle_b32 v103, v91 offset:swizzle(SWAP,16)
	v_mov_b32_e32 v97, v94
	s_and_saveexec_b64 s[28:29], vcc
	s_xor_b64 s[28:29], exec, s[28:29]
	s_cbranch_execz .LBB0_281
	v_cmp_eq_u32_e32 vcc, 1, v175
	s_and_saveexec_b64 s[30:31], vcc
	s_cbranch_execz .LBB0_280
	s_waitcnt vmcnt(1)
	v_pk_mul_f32 v[42:43], v[50:51], v[90:91]
	v_pk_mul_f32 v[48:49], v[48:49], v[92:93]
	s_waitcnt vmcnt(0) lgkmcnt(0)
	v_pk_fma_f32 v[90:91], v[46:47], v[102:103], v[42:43]
	v_pk_fma_f32 v[92:93], v[44:45], v[40:41], v[48:49]

.LBB0_290:
	v_mul_lo_u32 v42, s27, v80
	v_mul_lo_u32 v43, s26, v81
	v_mad_u64_u32 v[40:41], s[28:29], s26, v80, 0
	v_add3_u32 v41, v41, v43, v42
	s_waitcnt lgkmcnt(2)
	v_lshl_add_u64 v[44:45], v[40:41], 1, v[144:145]
	v_cvt_pk_bf16_f32 v40, v92, v93
	v_cvt_pk_bf16_f32 v41, v90, v91
	v_cvt_pk_bf16_f32 v42, v88, v89
	v_cvt_pk_bf16_f32 v43, v86, v87
	global_store_dwordx4 v[44:45], v[40:43], off nt
	s_and_b64 vcc, exec, s[4:5]
	s_nop 0
	v_cvt_pk_bf16_f32 v40, v84, v85
	v_cvt_pk_bf16_f32 v41, v82, v83
	v_cvt_pk_bf16_f32 v42, v54, v55
	v_cvt_pk_bf16_f32 v43, v52, v53
	global_store_dwordx4 v[44:45], v[40:43], off offset:64 nt
	s_nop 1
	v_add_u32_e32 v40, 0xa0, v180
	v_ashrrev_i32_e32 v41, 31, v40
	v_lshl_add_u64 v[42:43], v[40:41], 2, s[42:43]
	global_load_dword v42, v[42:43], off
	s_waitcnt vmcnt(0)
	v_fmamk_f32 v42, v42, 0x3a800000, v204
	v_rsq_f32_e32 v54, v42
	s_nop 0
	v_pk_fma_f32 v[50:51], v[30:31], v[54:55], v[78:79] op_sel_hi:[1,0,1]
	v_pk_fma_f32 v[52:53], v[28:29], v[54:55], v[76:77] op_sel_hi:[1,0,1]
	v_pk_fma_f32 v[46:47], v[26:27], v[54:55], v[74:75] op_sel_hi:[1,0,1]
	v_pk_fma_f32 v[48:49], v[24:25], v[54:55], v[72:73] op_sel_hi:[1,0,1]
	v_pk_fma_f32 v[42:43], v[22:23], v[54:55], v[70:71] op_sel_hi:[1,0,1]
	v_pk_fma_f32 v[44:45], v[20:21], v[54:55], v[68:69] op_sel_hi:[1,0,1]
	v_pk_fma_f32 v[28:29], v[18:19], v[54:55], v[66:67] op_sel_hi:[1,0,1]
	v_pk_fma_f32 v[30:31], v[16:17], v[54:55], v[64:65] op_sel_hi:[1,0,1]
	s_cbranch_vccnz .LBB0_304
	v_pk_mul_f32 v[16:17], v[50:51], v[50:51]
	v_pk_mul_f32 v[18:19], v[52:53], v[52:53]
	v_cmp_lt_i32_e32 vcc, 0, v175
	v_pk_mov_b32 v[20:21], v[18:19], v[16:17] op_sel:[1,0]
	v_mov_b32_e32 v19, v17
	v_pk_add_f32 v[16:17], v[20:21], v[18:19]
	v_pk_mul_f32 v[18:19], v[46:47], v[46:47]
	v_pk_add_f32 v[16:17], v[16:17], v[16:17] op_sel_hi:[0,1]
	v_pk_mul_f32 v[20:21], v[48:49], v[48:49]
	v_mul_f32_e32 v16, v44, v44
	v_pk_mov_b32 v[22:23], v[20:21], v[18:19] op_sel:[1,0]
	v_mov_b32_e32 v21, v19
	v_pk_add_f32 v[18:19], v[22:23], v[20:21]
	v_pk_fma_f32 v[20:21], v[44:45], v[44:45], v[16:17] op_sel_hi:[1,1,0]
	v_mul_f32_e32 v16, v42, v42
	v_pk_add_f32 v[18:19], v[18:19], v[18:19] op_sel_hi:[0,1]
	v_pk_fma_f32 v[22:23], v[42:43], v[42:43], v[16:17] op_sel_hi:[1,1,0]
	v_mul_f32_e32 v20, v30, v30
	v_mul_f32_e32 v22, v31, v31
	v_mul_f32_e32 v16, v28, v28
	v_mul_f32_e32 v18, v29, v29
	v_pk_add_f32 v[20:21], v[20:21], v[22:23]
	v_pk_add_f32 v[16:17], v[16:17], v[18:19]
	v_pk_mul_f32 v[18:19], v[60:61], v[52:53]
	v_pk_add_f32 v[16:17], v[20:21], v[16:17]
	s_nop 0
	v_add_f32_e32 v16, v16, v17
	ds_swizzle_b32 v17, v16 offset:swizzle(SWAP,16)
	s_waitcnt lgkmcnt(0)
	v_add_f32_e32 v16, v16, v17
	v_mov_b32_e32 v17, v16
	s_nop 1
	v_permlane32_swap_b32_e32 v16, v17
	v_add_f32_e32 v16, v16, v17
	v_fmamk_f32 v16, v16, 0x3c800000, v204
	v_rsq_f32_e32 v16, v16
	s_nop 0
	v_mul_f32_e32 v54, s19, v16
	v_mov_b32_e32 v55, v54
	v_pk_mul_f32 v[52:53], v[18:19], v[54:55] op_sel_hi:[1,0]
	v_lshlrev_b64 v[18:19], 5, v[40:41]
	v_lshl_add_u64 v[82:83], s[50:51], 0, v[18:19]
	v_lshl_add_u64 v[84:85], s[60:61], 0, v[18:19]
	global_load_dwordx4 v[24:27], v[82:83], off
	global_load_dwordx4 v[20:23], v[84:85], off
	v_pk_mul_f32 v[16:17], v[62:63], v[50:51]
	v_mov_b32_e32 v80, v54
	v_pk_mul_f32 v[50:51], v[16:17], v[54:55] op_sel_hi:[1,0]
	ds_swizzle_b32 v16, v52 offset:swizzle(SWAP,16)
	ds_swizzle_b32 v17, v53 offset:swizzle(SWAP,16)
	ds_swizzle_b32 v86, v50 offset:swizzle(SWAP,16)
	ds_swizzle_b32 v87, v51 offset:swizzle(SWAP,16)
	v_mov_b32_e32 v81, v54
	s_and_saveexec_b64 s[28:29], vcc
	s_xor_b64 s[28:29], exec, s[28:29]
	s_cbranch_execz .LBB0_295
	v_cmp_eq_u32_e32 vcc, 1, v175
	s_and_saveexec_b64 s[30:31], vcc
	s_cbranch_execz .LBB0_294
	s_waitcnt vmcnt(1)
	v_pk_mul_f32 v[18:19], v[26:27], v[50:51]
	v_pk_mul_f32 v[24:25], v[24:25], v[52:53]
	s_waitcnt vmcnt(0) lgkmcnt(0)
	v_pk_fma_f32 v[50:51], v[22:23], v[86:87], v[18:19]
	v_pk_fma_f32 v[52:53], v[20:21], v[16:17], v[24:25]

.LBB0_304:
	v_mul_lo_u32 v18, s27, v40
	v_mul_lo_u32 v19, s26, v41
	v_mad_u64_u32 v[16:17], s[28:29], s26, v40, 0
	v_add3_u32 v17, v17, v19, v18
	s_waitcnt lgkmcnt(2)
	v_lshl_add_u64 v[20:21], v[16:17], 1, v[144:145]
	v_cvt_pk_bf16_f32 v16, v52, v53
	v_cvt_pk_bf16_f32 v17, v50, v51
	v_cvt_pk_bf16_f32 v18, v48, v49
	v_cvt_pk_bf16_f32 v19, v46, v47
	global_store_dwordx4 v[20:21], v[16:19], off nt
	s_and_b64 vcc, exec, s[4:5]
	s_nop 0
	v_cvt_pk_bf16_f32 v16, v44, v45
	v_cvt_pk_bf16_f32 v17, v42, v43
	v_cvt_pk_bf16_f32 v18, v30, v31
	v_cvt_pk_bf16_f32 v19, v28, v29
	global_store_dwordx4 v[20:21], v[16:19], off offset:64 nt
	s_nop 1
	v_add_u32_e32 v16, 0xb0, v180
	v_ashrrev_i32_e32 v17, 31, v16
	v_lshl_add_u64 v[18:19], v[16:17], 2, s[42:43]
	global_load_dword v18, v[18:19], off
	s_waitcnt vmcnt(0)
	v_fmamk_f32 v18, v18, 0x3a800000, v204
	v_rsq_f32_e32 v30, v18
	s_nop 0
	v_pk_fma_f32 v[26:27], v[14:15], v[30:31], v[78:79] op_sel_hi:[1,0,1]
	v_pk_fma_f32 v[28:29], v[12:13], v[30:31], v[76:77] op_sel_hi:[1,0,1]
	v_pk_fma_f32 v[22:23], v[10:11], v[30:31], v[74:75] op_sel_hi:[1,0,1]
	v_pk_fma_f32 v[24:25], v[8:9], v[30:31], v[72:73] op_sel_hi:[1,0,1]
	v_pk_fma_f32 v[18:19], v[6:7], v[30:31], v[70:71] op_sel_hi:[1,0,1]
	v_pk_fma_f32 v[20:21], v[4:5], v[30:31], v[68:69] op_sel_hi:[1,0,1]
	v_pk_fma_f32 v[12:13], v[2:3], v[30:31], v[66:67] op_sel_hi:[1,0,1]
	v_pk_fma_f32 v[14:15], v[0:1], v[30:31], v[64:65] op_sel_hi:[1,0,1]
	s_cbranch_vccnz .LBB0_318
	v_pk_mul_f32 v[0:1], v[26:27], v[26:27]
	v_pk_mul_f32 v[2:3], v[28:29], v[28:29]
	v_cmp_lt_i32_e32 vcc, 0, v175
	v_pk_mov_b32 v[4:5], v[2:3], v[0:1] op_sel:[1,0]
	v_mov_b32_e32 v3, v1
	v_pk_add_f32 v[0:1], v[4:5], v[2:3]
	v_pk_mul_f32 v[2:3], v[22:23], v[22:23]
	v_pk_add_f32 v[0:1], v[0:1], v[0:1] op_sel_hi:[0,1]
	v_pk_mul_f32 v[4:5], v[24:25], v[24:25]
	v_mul_f32_e32 v0, v20, v20
	v_pk_mov_b32 v[6:7], v[4:5], v[2:3] op_sel:[1,0]
	v_mov_b32_e32 v5, v3
	v_pk_add_f32 v[2:3], v[6:7], v[4:5]
	v_pk_fma_f32 v[4:5], v[20:21], v[20:21], v[0:1] op_sel_hi:[1,1,0]
	v_mul_f32_e32 v0, v18, v18
	v_pk_add_f32 v[2:3], v[2:3], v[2:3] op_sel_hi:[0,1]
	v_pk_fma_f32 v[6:7], v[18:19], v[18:19], v[0:1] op_sel_hi:[1,1,0]
	v_mul_f32_e32 v4, v14, v14
	v_mul_f32_e32 v6, v15, v15
	v_mul_f32_e32 v0, v12, v12
	v_mul_f32_e32 v2, v13, v13
	v_pk_add_f32 v[4:5], v[4:5], v[6:7]
	v_pk_add_f32 v[0:1], v[0:1], v[2:3]
	v_pk_mul_f32 v[2:3], v[60:61], v[28:29]
	v_pk_add_f32 v[0:1], v[4:5], v[0:1]
	s_nop 0
	v_add_f32_e32 v0, v0, v1
	ds_swizzle_b32 v1, v0 offset:swizzle(SWAP,16)
	s_waitcnt lgkmcnt(0)
	v_add_f32_e32 v0, v0, v1
	v_mov_b32_e32 v1, v0
	s_nop 1
	v_permlane32_swap_b32_e32 v0, v1
	v_add_f32_e32 v0, v0, v1
	v_fmamk_f32 v0, v0, 0x3c800000, v204
	v_rsq_f32_e32 v0, v0
	s_nop 0
	v_mul_f32_e32 v30, s19, v0
	v_mov_b32_e32 v31, v30
	v_pk_mul_f32 v[28:29], v[2:3], v[30:31] op_sel_hi:[1,0]
	v_lshlrev_b64 v[2:3], 5, v[16:17]
	v_lshl_add_u64 v[42:43], s[50:51], 0, v[2:3]
	v_lshl_add_u64 v[44:45], s[60:61], 0, v[2:3]
	global_load_dwordx4 v[8:11], v[42:43], off
	global_load_dwordx4 v[4:7], v[44:45], off
	v_pk_mul_f32 v[0:1], v[62:63], v[26:27]
	v_mov_b32_e32 v40, v30
	v_pk_mul_f32 v[26:27], v[0:1], v[30:31] op_sel_hi:[1,0]
	ds_swizzle_b32 v0, v28 offset:swizzle(SWAP,16)
	ds_swizzle_b32 v1, v29 offset:swizzle(SWAP,16)
	ds_swizzle_b32 v46, v26 offset:swizzle(SWAP,16)
	ds_swizzle_b32 v47, v27 offset:swizzle(SWAP,16)
	v_mov_b32_e32 v41, v30
	s_and_saveexec_b64 s[4:5], vcc
	s_xor_b64 s[4:5], exec, s[4:5]
	s_cbranch_execz .LBB0_309
	v_cmp_eq_u32_e32 vcc, 1, v175
	s_and_saveexec_b64 s[28:29], vcc
	s_cbranch_execz .LBB0_308
	s_waitcnt vmcnt(1)
	v_pk_mul_f32 v[2:3], v[10:11], v[26:27]
	v_pk_mul_f32 v[8:9], v[8:9], v[28:29]
	s_waitcnt vmcnt(0) lgkmcnt(0)
	v_pk_fma_f32 v[26:27], v[6:7], v[46:47], v[2:3]
	v_pk_fma_f32 v[28:29], v[4:5], v[0:1], v[8:9]

.LBB0_318:
	v_mul_lo_u32 v2, s27, v16
	v_mul_lo_u32 v3, s26, v17
	v_mad_u64_u32 v[0:1], s[4:5], s26, v16, 0
	v_add3_u32 v1, v1, v3, v2
	s_waitcnt lgkmcnt(2)
	v_lshl_add_u64 v[4:5], v[0:1], 1, v[144:145]
	v_cvt_pk_bf16_f32 v0, v28, v29
	v_cvt_pk_bf16_f32 v1, v26, v27
	v_cvt_pk_bf16_f32 v2, v24, v25
	v_cvt_pk_bf16_f32 v3, v22, v23
	s_andn2_b64 vcc, exec, s[2:3]
	s_mov_b64 s[2:3], -1
	global_store_dwordx4 v[4:5], v[0:3], off nt
	s_nop 1
	v_cvt_pk_bf16_f32 v0, v20, v21
	v_cvt_pk_bf16_f32 v1, v18, v19
	v_cvt_pk_bf16_f32 v2, v14, v15
	v_cvt_pk_bf16_f32 v3, v12, v13
	global_store_dwordx4 v[4:5], v[0:3], off offset:64 nt
	s_cbranch_vccnz .LBB0_181
	s_andn2_b64 vcc, exec, s[0:1]
	s_cbranch_vccnz .LBB0_180
	s_barrier
	s_branch .LBB0_180

.LBB0_728:
	s_ashr_i32 s18, s2, 4
	s_ashr_i32 s19, s18, 31
	s_lshl_b64 s[18:19], s[18:19], 14
	v_lshl_or_b32 v162, s3, 8, v158
	s_add_u32 s18, s31, s18
	v_lshl_add_u32 v154, s2, 8, v156
	s_addc_u32 s19, s34, s19
	v_ashrrev_i32_e32 v163, 31, v162
	v_ashrrev_i32_e32 v155, 31, v154
	v_lshl_add_u64 v[36:37], v[162:163], 2, s[18:19]
	v_lshl_add_u64 v[166:167], v[154:155], 2, s[50:51]
	global_load_dwordx4 v[40:43], v[36:37], off offset:16
	global_load_dwordx4 v[44:47], v[36:37], off
	global_load_dwordx4 v[32:35], v[36:37], off offset:528
	s_nop 0
	global_load_dwordx4 v[36:39], v[36:37], off offset:512
	v_lshlrev_b64 v[168:169], 13, v[154:155]
	global_load_dword v170, v[166:167], off
	global_load_dword v171, v[166:167], off offset:64
	global_load_dword v172, v[166:167], off offset:128
	global_load_dword v173, v[166:167], off offset:192
	global_load_dword v174, v[166:167], off offset:512
	global_load_dword v175, v[166:167], off offset:576
	global_load_dword v176, v[166:167], off offset:640
	global_load_dword v177, v[166:167], off offset:704
	s_mov_b64 s[18:19], -1
	s_andn2_b64 vcc, exec, s[4:5]
	s_waitcnt vmcnt(0)
	v_fmamk_f32 v166, v170, 0x3a800000, v204
	v_rsq_f32_e32 v166, v166
	s_nop 0
	v_pk_fma_f32 v[138:139], v[138:139], v[166:167], v[42:43] op_sel_hi:[1,0,1]
	v_pk_fma_f32 v[142:143], v[142:143], v[166:167], v[46:47] op_sel_hi:[1,0,1]
	v_pk_fma_f32 v[140:141], v[140:141], v[166:167], v[44:45] op_sel_hi:[1,0,1]
	v_pk_fma_f32 v[136:137], v[136:137], v[166:167], v[40:41] op_sel_hi:[1,0,1]
	v_max_f32_e32 v138, 0, v138
	v_max_f32_e32 v140, 0, v140
	v_max_f32_e32 v142, 0, v142
	v_max_f32_e32 v143, 0, v143
	v_max_f32_e32 v136, 0, v136
	v_max_f32_e32 v137, 0, v137
	v_mul_f32_e32 v155, v138, v138
	v_max_f32_e32 v138, 0, v139
	v_mul_f32_e32 v140, v140, v140
	v_max_f32_e32 v141, 0, v141
	v_mul_f32_e32 v142, v142, v142
	v_mul_f32_e32 v143, v143, v143
	v_mul_f32_e32 v136, v136, v136
	v_mul_f32_e32 v137, v137, v137
	v_mul_f32_e32 v167, v138, v138
	v_mul_f32_e32 v141, v141, v141
	v_cvt_pk_bf16_f32 v138, v140, v141
	v_cvt_pk_bf16_f32 v139, v142, v143
	v_cvt_pk_bf16_f32 v140, v136, v137
	v_lshl_add_u64 v[142:143], s[62:63], 0, v[168:169]
	v_lshlrev_b64 v[136:137], 1, v[162:163]
	v_pk_fma_f32 v[128:129], v[128:129], v[166:167], v[32:33] op_sel_hi:[1,0,1]
	v_lshl_add_u64 v[142:143], v[142:143], 0, v[136:137]
	v_max_f32_e32 v128, 0, v128
	v_cvt_pk_bf16_f32 v141, v155, v167
	global_store_dwordx4 v[142:143], v[138:141], off nt
	v_pk_fma_f32 v[130:131], v[130:131], v[166:167], v[34:35] op_sel_hi:[1,0,1]
	v_pk_fma_f32 v[132:133], v[132:133], v[166:167], v[36:37] op_sel_hi:[1,0,1]
	v_mul_f32_e32 v138, v128, v128
	v_max_f32_e32 v128, 0, v129
	v_mul_f32_e32 v139, v128, v128
	v_max_f32_e32 v128, 0, v130
	v_pk_fma_f32 v[134:135], v[134:135], v[166:167], v[38:39] op_sel_hi:[1,0,1]
	v_max_f32_e32 v132, 0, v132
	v_max_f32_e32 v133, 0, v133
	v_mul_f32_e32 v140, v128, v128
	v_max_f32_e32 v128, 0, v131
	v_mul_f32_e32 v132, v132, v132
	v_mul_f32_e32 v133, v133, v133
	v_max_f32_e32 v134, 0, v134
	v_max_f32_e32 v135, 0, v135
	v_mul_f32_e32 v131, v128, v128
	v_cvt_pk_bf16_f32 v128, v132, v133
	v_mul_f32_e32 v134, v134, v134
	v_mul_f32_e32 v135, v135, v135
	v_cvt_pk_bf16_f32 v129, v134, v135
	v_cvt_pk_bf16_f32 v130, v138, v139
	v_cvt_pk_bf16_f32 v131, v140, v131
	global_store_dwordx4 v[142:143], v[128:131], off offset:256 nt
	s_nop 1
	v_or_b32_e32 v128, 16, v154
	v_ashrrev_i32_e32 v129, 31, v128
	v_lshlrev_b64 v[128:129], 13, v[128:129]
	v_fmamk_f32 v130, v171, 0x3a800000, v204
	v_rsq_f32_e32 v130, v130
	s_nop 0
	v_pk_fma_f32 v[120:121], v[120:121], v[130:131], v[40:41] op_sel_hi:[1,0,1]
	s_nop 0
	v_max_f32_e32 v120, 0, v120
	v_pk_fma_f32 v[126:127], v[126:127], v[130:131], v[46:47] op_sel_hi:[1,0,1]
	v_pk_fma_f32 v[124:125], v[124:125], v[130:131], v[44:45] op_sel_hi:[1,0,1]
	v_pk_fma_f32 v[122:123], v[122:123], v[130:131], v[42:43] op_sel_hi:[1,0,1]
	v_mul_f32_e32 v131, v120, v120
	v_max_f32_e32 v120, 0, v121
	v_max_f32_e32 v124, 0, v124
	v_max_f32_e32 v125, 0, v125
	v_mul_f32_e32 v132, v120, v120
	v_max_f32_e32 v120, 0, v122
	v_mul_f32_e32 v124, v124, v124
	v_mul_f32_e32 v125, v125, v125
	v_mul_f32_e32 v133, v120, v120
	v_max_f32_e32 v120, 0, v123
	v_mul_f32_e32 v123, v120, v120
	v_cvt_pk_bf16_f32 v120, v124, v125
	v_lshl_add_u64 v[124:125], s[62:63], 0, v[128:129]
	v_pk_fma_f32 v[112:113], v[112:113], v[130:131], v[32:33] op_sel_hi:[1,0,1]
	v_max_f32_e32 v126, 0, v126
	v_max_f32_e32 v127, 0, v127
	v_lshl_add_u64 v[124:125], v[124:125], 0, v[136:137]
	v_max_f32_e32 v112, 0, v112
	v_mul_f32_e32 v126, v126, v126
	v_mul_f32_e32 v127, v127, v127
	v_cvt_pk_bf16_f32 v121, v126, v127
	v_cvt_pk_bf16_f32 v122, v131, v132
	v_cvt_pk_bf16_f32 v123, v133, v123
	global_store_dwordx4 v[124:125], v[120:123], off nt
	v_pk_fma_f32 v[114:115], v[114:115], v[130:131], v[34:35] op_sel_hi:[1,0,1]
	v_pk_fma_f32 v[116:117], v[116:117], v[130:131], v[36:37] op_sel_hi:[1,0,1]
	v_mul_f32_e32 v120, v112, v112
	v_max_f32_e32 v112, 0, v113
	v_mul_f32_e32 v121, v112, v112
	v_max_f32_e32 v112, 0, v114
	v_pk_fma_f32 v[118:119], v[118:119], v[130:131], v[38:39] op_sel_hi:[1,0,1]
	v_max_f32_e32 v116, 0, v116
	v_max_f32_e32 v117, 0, v117
	v_mul_f32_e32 v122, v112, v112
	v_max_f32_e32 v112, 0, v115
	v_mul_f32_e32 v116, v116, v116
	v_mul_f32_e32 v117, v117, v117
	v_max_f32_e32 v118, 0, v118
	v_max_f32_e32 v119, 0, v119
	v_mul_f32_e32 v115, v112, v112
	v_cvt_pk_bf16_f32 v112, v116, v117
	v_mul_f32_e32 v118, v118, v118
	v_mul_f32_e32 v119, v119, v119
	v_cvt_pk_bf16_f32 v113, v118, v119
	v_cvt_pk_bf16_f32 v114, v120, v121
	v_cvt_pk_bf16_f32 v115, v122, v115
	global_store_dwordx4 v[124:125], v[112:115], off offset:256 nt
	s_nop 1
	v_or_b32_e32 v112, 32, v154
	v_ashrrev_i32_e32 v113, 31, v112
	v_lshlrev_b64 v[112:113], 13, v[112:113]
	v_fmamk_f32 v114, v172, 0x3a800000, v204
	v_rsq_f32_e32 v114, v114
	s_nop 0
	v_pk_fma_f32 v[104:105], v[104:105], v[114:115], v[40:41] op_sel_hi:[1,0,1]
	s_nop 0
	v_max_f32_e32 v104, 0, v104
	v_pk_fma_f32 v[110:111], v[110:111], v[114:115], v[46:47] op_sel_hi:[1,0,1]
	v_pk_fma_f32 v[108:109], v[108:109], v[114:115], v[44:45] op_sel_hi:[1,0,1]
	v_pk_fma_f32 v[106:107], v[106:107], v[114:115], v[42:43] op_sel_hi:[1,0,1]
	v_mul_f32_e32 v115, v104, v104
	v_max_f32_e32 v104, 0, v105
	v_max_f32_e32 v108, 0, v108
	v_max_f32_e32 v109, 0, v109
	v_mul_f32_e32 v116, v104, v104
	v_max_f32_e32 v104, 0, v106
	v_mul_f32_e32 v108, v108, v108
	v_mul_f32_e32 v109, v109, v109
	v_mul_f32_e32 v117, v104, v104
	v_max_f32_e32 v104, 0, v107
	v_mul_f32_e32 v107, v104, v104
	v_cvt_pk_bf16_f32 v104, v108, v109
	v_lshl_add_u64 v[108:109], s[62:63], 0, v[112:113]
	v_pk_fma_f32 v[96:97], v[96:97], v[114:115], v[32:33] op_sel_hi:[1,0,1]
	v_max_f32_e32 v110, 0, v110
	v_max_f32_e32 v111, 0, v111
	v_lshl_add_u64 v[108:109], v[108:109], 0, v[136:137]
	v_max_f32_e32 v96, 0, v96
	v_mul_f32_e32 v110, v110, v110
	v_mul_f32_e32 v111, v111, v111
	v_cvt_pk_bf16_f32 v105, v110, v111
	v_cvt_pk_bf16_f32 v106, v115, v116
	v_cvt_pk_bf16_f32 v107, v117, v107
	global_store_dwordx4 v[108:109], v[104:107], off nt
	v_pk_fma_f32 v[98:99], v[98:99], v[114:115], v[34:35] op_sel_hi:[1,0,1]
	v_pk_fma_f32 v[100:101], v[100:101], v[114:115], v[36:37] op_sel_hi:[1,0,1]
	v_mul_f32_e32 v104, v96, v96
	v_max_f32_e32 v96, 0, v97
	v_mul_f32_e32 v105, v96, v96
	v_max_f32_e32 v96, 0, v98
	v_pk_fma_f32 v[102:103], v[102:103], v[114:115], v[38:39] op_sel_hi:[1,0,1]
	v_max_f32_e32 v100, 0, v100
	v_max_f32_e32 v101, 0, v101
	v_mul_f32_e32 v106, v96, v96
	v_max_f32_e32 v96, 0, v99
	v_mul_f32_e32 v100, v100, v100
	v_mul_f32_e32 v101, v101, v101
	v_max_f32_e32 v102, 0, v102
	v_max_f32_e32 v103, 0, v103
	v_mul_f32_e32 v99, v96, v96
	v_cvt_pk_bf16_f32 v96, v100, v101
	v_mul_f32_e32 v102, v102, v102
	v_mul_f32_e32 v103, v103, v103
	v_cvt_pk_bf16_f32 v97, v102, v103
	v_cvt_pk_bf16_f32 v98, v104, v105
	v_cvt_pk_bf16_f32 v99, v106, v99
	global_store_dwordx4 v[108:109], v[96:99], off offset:256 nt
	s_nop 1
	v_or_b32_e32 v96, 48, v154
	v_ashrrev_i32_e32 v97, 31, v96
	v_lshlrev_b64 v[96:97], 13, v[96:97]
	v_fmamk_f32 v98, v173, 0x3a800000, v204
	v_rsq_f32_e32 v98, v98
	s_nop 0
	v_pk_fma_f32 v[88:89], v[88:89], v[98:99], v[40:41] op_sel_hi:[1,0,1]
	s_nop 0
	v_max_f32_e32 v88, 0, v88
	v_pk_fma_f32 v[94:95], v[94:95], v[98:99], v[46:47] op_sel_hi:[1,0,1]
	v_pk_fma_f32 v[92:93], v[92:93], v[98:99], v[44:45] op_sel_hi:[1,0,1]
	v_pk_fma_f32 v[90:91], v[90:91], v[98:99], v[42:43] op_sel_hi:[1,0,1]
	v_mul_f32_e32 v99, v88, v88
	v_max_f32_e32 v88, 0, v89
	v_max_f32_e32 v92, 0, v92
	v_max_f32_e32 v93, 0, v93
	v_mul_f32_e32 v100, v88, v88
	v_max_f32_e32 v88, 0, v90
	v_mul_f32_e32 v92, v92, v92
	v_mul_f32_e32 v93, v93, v93
	v_mul_f32_e32 v101, v88, v88
	v_max_f32_e32 v88, 0, v91
	v_mul_f32_e32 v91, v88, v88
	v_cvt_pk_bf16_f32 v88, v92, v93
	v_lshl_add_u64 v[92:93], s[62:63], 0, v[96:97]
	v_pk_fma_f32 v[80:81], v[80:81], v[98:99], v[32:33] op_sel_hi:[1,0,1]
	v_max_f32_e32 v94, 0, v94
	v_max_f32_e32 v95, 0, v95
	v_lshl_add_u64 v[92:93], v[92:93], 0, v[136:137]
	v_max_f32_e32 v80, 0, v80
	v_mul_f32_e32 v94, v94, v94
	v_mul_f32_e32 v95, v95, v95
	v_cvt_pk_bf16_f32 v89, v94, v95
	v_cvt_pk_bf16_f32 v90, v99, v100
	v_cvt_pk_bf16_f32 v91, v101, v91
	global_store_dwordx4 v[92:93], v[88:91], off nt
	v_pk_fma_f32 v[82:83], v[82:83], v[98:99], v[34:35] op_sel_hi:[1,0,1]
	v_pk_fma_f32 v[84:85], v[84:85], v[98:99], v[36:37] op_sel_hi:[1,0,1]
	v_mul_f32_e32 v88, v80, v80
	v_max_f32_e32 v80, 0, v81
	v_mul_f32_e32 v89, v80, v80
	v_max_f32_e32 v80, 0, v82
	v_pk_fma_f32 v[86:87], v[86:87], v[98:99], v[38:39] op_sel_hi:[1,0,1]
	v_max_f32_e32 v84, 0, v84
	v_max_f32_e32 v85, 0, v85
	v_mul_f32_e32 v90, v80, v80
	v_max_f32_e32 v80, 0, v83
	v_mul_f32_e32 v84, v84, v84
	v_mul_f32_e32 v85, v85, v85
	v_max_f32_e32 v86, 0, v86
	v_max_f32_e32 v87, 0, v87
	v_mul_f32_e32 v83, v80, v80
	v_cvt_pk_bf16_f32 v80, v84, v85
	v_mul_f32_e32 v86, v86, v86
	v_mul_f32_e32 v87, v87, v87
	v_cvt_pk_bf16_f32 v81, v86, v87
	v_cvt_pk_bf16_f32 v82, v88, v89
	v_cvt_pk_bf16_f32 v83, v90, v83
	global_store_dwordx4 v[92:93], v[80:83], off offset:256 nt
	s_nop 1
	v_add_u32_e32 v80, 0x80, v154
	v_ashrrev_i32_e32 v81, 31, v80
	v_lshlrev_b64 v[80:81], 13, v[80:81]
	v_fmamk_f32 v82, v174, 0x3a800000, v204
	v_rsq_f32_e32 v82, v82
	s_nop 0
	v_pk_fma_f32 v[72:73], v[72:73], v[82:83], v[40:41] op_sel_hi:[1,0,1]
	s_nop 0
	v_max_f32_e32 v72, 0, v72
	v_pk_fma_f32 v[78:79], v[78:79], v[82:83], v[46:47] op_sel_hi:[1,0,1]
	v_pk_fma_f32 v[76:77], v[76:77], v[82:83], v[44:45] op_sel_hi:[1,0,1]
	v_pk_fma_f32 v[74:75], v[74:75], v[82:83], v[42:43] op_sel_hi:[1,0,1]
	v_mul_f32_e32 v83, v72, v72
	v_max_f32_e32 v72, 0, v73
	v_max_f32_e32 v76, 0, v76
	v_max_f32_e32 v77, 0, v77
	v_mul_f32_e32 v84, v72, v72
	v_max_f32_e32 v72, 0, v74
	v_mul_f32_e32 v76, v76, v76
	v_mul_f32_e32 v77, v77, v77
	v_mul_f32_e32 v85, v72, v72
	v_max_f32_e32 v72, 0, v75
	v_mul_f32_e32 v75, v72, v72
	v_cvt_pk_bf16_f32 v72, v76, v77
	v_lshl_add_u64 v[76:77], s[62:63], 0, v[80:81]
	v_pk_fma_f32 v[64:65], v[64:65], v[82:83], v[32:33] op_sel_hi:[1,0,1]
	v_max_f32_e32 v78, 0, v78
	v_max_f32_e32 v79, 0, v79
	v_lshl_add_u64 v[76:77], v[76:77], 0, v[136:137]
	v_max_f32_e32 v64, 0, v64
	v_mul_f32_e32 v78, v78, v78
	v_mul_f32_e32 v79, v79, v79
	v_cvt_pk_bf16_f32 v73, v78, v79
	v_cvt_pk_bf16_f32 v74, v83, v84
	v_cvt_pk_bf16_f32 v75, v85, v75
	global_store_dwordx4 v[76:77], v[72:75], off nt
	v_pk_fma_f32 v[66:67], v[66:67], v[82:83], v[34:35] op_sel_hi:[1,0,1]
	v_pk_fma_f32 v[68:69], v[68:69], v[82:83], v[36:37] op_sel_hi:[1,0,1]
	v_mul_f32_e32 v72, v64, v64
	v_max_f32_e32 v64, 0, v65
	v_mul_f32_e32 v73, v64, v64
	v_max_f32_e32 v64, 0, v66
	v_pk_fma_f32 v[70:71], v[70:71], v[82:83], v[38:39] op_sel_hi:[1,0,1]
	v_max_f32_e32 v68, 0, v68
	v_max_f32_e32 v69, 0, v69
	v_mul_f32_e32 v74, v64, v64
	v_max_f32_e32 v64, 0, v67
	v_mul_f32_e32 v68, v68, v68
	v_mul_f32_e32 v69, v69, v69
	v_max_f32_e32 v70, 0, v70
	v_max_f32_e32 v71, 0, v71
	v_mul_f32_e32 v67, v64, v64
	v_cvt_pk_bf16_f32 v64, v68, v69
	v_mul_f32_e32 v70, v70, v70
	v_mul_f32_e32 v71, v71, v71
	v_cvt_pk_bf16_f32 v65, v70, v71
	v_cvt_pk_bf16_f32 v66, v72, v73
	v_cvt_pk_bf16_f32 v67, v74, v67
	global_store_dwordx4 v[76:77], v[64:67], off offset:256 nt
	s_nop 1
	v_add_u32_e32 v64, 0x90, v154
	v_ashrrev_i32_e32 v65, 31, v64
	v_lshlrev_b64 v[64:65], 13, v[64:65]
	v_fmamk_f32 v66, v175, 0x3a800000, v204
	v_rsq_f32_e32 v66, v66
	s_nop 0
	v_pk_fma_f32 v[56:57], v[56:57], v[66:67], v[40:41] op_sel_hi:[1,0,1]
	s_nop 0
	v_max_f32_e32 v56, 0, v56
	v_pk_fma_f32 v[62:63], v[62:63], v[66:67], v[46:47] op_sel_hi:[1,0,1]
	v_pk_fma_f32 v[60:61], v[60:61], v[66:67], v[44:45] op_sel_hi:[1,0,1]
	v_pk_fma_f32 v[58:59], v[58:59], v[66:67], v[42:43] op_sel_hi:[1,0,1]
	v_mul_f32_e32 v67, v56, v56
	v_max_f32_e32 v56, 0, v57
	v_max_f32_e32 v60, 0, v60
	v_max_f32_e32 v61, 0, v61
	v_mul_f32_e32 v68, v56, v56
	v_max_f32_e32 v56, 0, v58
	v_mul_f32_e32 v60, v60, v60
	v_mul_f32_e32 v61, v61, v61
	v_mul_f32_e32 v69, v56, v56
	v_max_f32_e32 v56, 0, v59
	v_mul_f32_e32 v59, v56, v56
	v_cvt_pk_bf16_f32 v56, v60, v61
	v_lshl_add_u64 v[60:61], s[62:63], 0, v[64:65]
	v_pk_fma_f32 v[48:49], v[48:49], v[66:67], v[32:33] op_sel_hi:[1,0,1]
	v_max_f32_e32 v62, 0, v62
	v_max_f32_e32 v63, 0, v63
	v_lshl_add_u64 v[60:61], v[60:61], 0, v[136:137]
	v_max_f32_e32 v48, 0, v48
	v_mul_f32_e32 v62, v62, v62
	v_mul_f32_e32 v63, v63, v63
	v_cvt_pk_bf16_f32 v57, v62, v63
	v_cvt_pk_bf16_f32 v58, v67, v68
	v_cvt_pk_bf16_f32 v59, v69, v59
	global_store_dwordx4 v[60:61], v[56:59], off nt
	v_pk_fma_f32 v[50:51], v[50:51], v[66:67], v[34:35] op_sel_hi:[1,0,1]
	v_pk_fma_f32 v[52:53], v[52:53], v[66:67], v[36:37] op_sel_hi:[1,0,1]
	v_mul_f32_e32 v56, v48, v48
	v_max_f32_e32 v48, 0, v49
	v_mul_f32_e32 v57, v48, v48
	v_max_f32_e32 v48, 0, v50
	v_pk_fma_f32 v[54:55], v[54:55], v[66:67], v[38:39] op_sel_hi:[1,0,1]
	v_max_f32_e32 v52, 0, v52
	v_max_f32_e32 v53, 0, v53
	v_mul_f32_e32 v58, v48, v48
	v_max_f32_e32 v48, 0, v51
	v_mul_f32_e32 v52, v52, v52
	v_mul_f32_e32 v53, v53, v53
	v_max_f32_e32 v54, 0, v54
	v_max_f32_e32 v55, 0, v55
	v_mul_f32_e32 v51, v48, v48
	v_cvt_pk_bf16_f32 v48, v52, v53
	v_mul_f32_e32 v54, v54, v54
	v_mul_f32_e32 v55, v55, v55
	v_cvt_pk_bf16_f32 v49, v54, v55
	v_cvt_pk_bf16_f32 v50, v56, v57
	v_cvt_pk_bf16_f32 v51, v58, v51
	global_store_dwordx4 v[60:61], v[48:51], off offset:256 nt
	s_nop 1
	v_add_u32_e32 v48, 0xa0, v154
	v_ashrrev_i32_e32 v49, 31, v48
	v_lshlrev_b64 v[48:49], 13, v[48:49]
	v_fmamk_f32 v50, v176, 0x3a800000, v204
	v_rsq_f32_e32 v50, v50
	s_nop 0
	v_pk_fma_f32 v[24:25], v[24:25], v[50:51], v[40:41] op_sel_hi:[1,0,1]
	s_nop 0
	v_max_f32_e32 v24, 0, v24
	v_pk_fma_f32 v[30:31], v[30:31], v[50:51], v[46:47] op_sel_hi:[1,0,1]
	v_pk_fma_f32 v[28:29], v[28:29], v[50:51], v[44:45] op_sel_hi:[1,0,1]
	v_pk_fma_f32 v[26:27], v[26:27], v[50:51], v[42:43] op_sel_hi:[1,0,1]
	v_mul_f32_e32 v51, v24, v24
	v_max_f32_e32 v24, 0, v25
	v_max_f32_e32 v28, 0, v28
	v_max_f32_e32 v29, 0, v29
	v_mul_f32_e32 v52, v24, v24
	v_max_f32_e32 v24, 0, v26
	v_mul_f32_e32 v28, v28, v28
	v_mul_f32_e32 v29, v29, v29
	v_mul_f32_e32 v53, v24, v24
	v_max_f32_e32 v24, 0, v27
	v_mul_f32_e32 v27, v24, v24
	v_cvt_pk_bf16_f32 v24, v28, v29
	v_lshl_add_u64 v[28:29], s[62:63], 0, v[48:49]
	v_pk_fma_f32 v[16:17], v[16:17], v[50:51], v[32:33] op_sel_hi:[1,0,1]
	v_max_f32_e32 v30, 0, v30
	v_max_f32_e32 v31, 0, v31
	v_lshl_add_u64 v[28:29], v[28:29], 0, v[136:137]
	v_max_f32_e32 v16, 0, v16
	v_mul_f32_e32 v30, v30, v30
	v_mul_f32_e32 v31, v31, v31
	v_cvt_pk_bf16_f32 v25, v30, v31
	v_cvt_pk_bf16_f32 v26, v51, v52
	v_cvt_pk_bf16_f32 v27, v53, v27
	global_store_dwordx4 v[28:29], v[24:27], off nt
	v_pk_fma_f32 v[18:19], v[18:19], v[50:51], v[34:35] op_sel_hi:[1,0,1]
	v_pk_fma_f32 v[20:21], v[20:21], v[50:51], v[36:37] op_sel_hi:[1,0,1]
	v_mul_f32_e32 v24, v16, v16
	v_max_f32_e32 v16, 0, v17
	v_mul_f32_e32 v25, v16, v16
	v_max_f32_e32 v16, 0, v18
	v_pk_fma_f32 v[22:23], v[22:23], v[50:51], v[38:39] op_sel_hi:[1,0,1]
	v_max_f32_e32 v20, 0, v20
	v_max_f32_e32 v21, 0, v21
	v_mul_f32_e32 v26, v16, v16
	v_max_f32_e32 v16, 0, v19
	v_mul_f32_e32 v20, v20, v20
	v_mul_f32_e32 v21, v21, v21
	v_max_f32_e32 v22, 0, v22
	v_max_f32_e32 v23, 0, v23
	v_mul_f32_e32 v19, v16, v16
	v_cvt_pk_bf16_f32 v16, v20, v21
	v_mul_f32_e32 v22, v22, v22
	v_mul_f32_e32 v23, v23, v23
	v_cvt_pk_bf16_f32 v17, v22, v23
	v_cvt_pk_bf16_f32 v18, v24, v25
	v_cvt_pk_bf16_f32 v19, v26, v19
	global_store_dwordx4 v[28:29], v[16:19], off offset:256 nt
	s_nop 1
	v_add_u32_e32 v16, 0xb0, v154
	v_ashrrev_i32_e32 v17, 31, v16
	v_lshlrev_b64 v[16:17], 13, v[16:17]
	v_fmamk_f32 v18, v177, 0x3a800000, v204
	v_rsq_f32_e32 v18, v18
	s_nop 0
	v_pk_fma_f32 v[8:9], v[8:9], v[18:19], v[40:41] op_sel_hi:[1,0,1]
	s_nop 0
	v_max_f32_e32 v8, 0, v8
	v_pk_fma_f32 v[14:15], v[14:15], v[18:19], v[46:47] op_sel_hi:[1,0,1]
	v_pk_fma_f32 v[12:13], v[12:13], v[18:19], v[44:45] op_sel_hi:[1,0,1]
	v_pk_fma_f32 v[10:11], v[10:11], v[18:19], v[42:43] op_sel_hi:[1,0,1]
	v_mul_f32_e32 v19, v8, v8
	v_max_f32_e32 v8, 0, v9
	v_max_f32_e32 v12, 0, v12
	v_max_f32_e32 v13, 0, v13
	v_mul_f32_e32 v20, v8, v8
	v_max_f32_e32 v8, 0, v10
	v_mul_f32_e32 v12, v12, v12
	v_mul_f32_e32 v13, v13, v13
	v_mul_f32_e32 v21, v8, v8
	v_max_f32_e32 v8, 0, v11
	v_mul_f32_e32 v11, v8, v8
	v_cvt_pk_bf16_f32 v8, v12, v13
	v_lshl_add_u64 v[12:13], s[62:63], 0, v[16:17]
	v_pk_fma_f32 v[0:1], v[0:1], v[18:19], v[32:33] op_sel_hi:[1,0,1]
	v_max_f32_e32 v14, 0, v14
	v_max_f32_e32 v15, 0, v15
	v_lshl_add_u64 v[12:13], v[12:13], 0, v[136:137]
	v_max_f32_e32 v0, 0, v0
	v_mul_f32_e32 v14, v14, v14
	v_mul_f32_e32 v15, v15, v15
	v_cvt_pk_bf16_f32 v9, v14, v15
	v_cvt_pk_bf16_f32 v10, v19, v20
	v_cvt_pk_bf16_f32 v11, v21, v11
	global_store_dwordx4 v[12:13], v[8:11], off nt
	v_pk_fma_f32 v[2:3], v[2:3], v[18:19], v[34:35] op_sel_hi:[1,0,1]
	v_pk_fma_f32 v[6:7], v[6:7], v[18:19], v[38:39] op_sel_hi:[1,0,1]
	v_mul_f32_e32 v8, v0, v0
	v_max_f32_e32 v0, 0, v1
	v_mul_f32_e32 v9, v0, v0
	v_max_f32_e32 v0, 0, v2
	v_pk_fma_f32 v[4:5], v[4:5], v[18:19], v[36:37] op_sel_hi:[1,0,1]
	v_mul_f32_e32 v10, v0, v0
	v_max_f32_e32 v0, 0, v3
	v_max_f32_e32 v4, 0, v4
	v_max_f32_e32 v5, 0, v5
	v_max_f32_e32 v6, 0, v6
	v_max_f32_e32 v7, 0, v7
	v_mul_f32_e32 v3, v0, v0
	v_mul_f32_e32 v4, v4, v4
	v_mul_f32_e32 v5, v5, v5
	v_mul_f32_e32 v6, v6, v6
	v_mul_f32_e32 v7, v7, v7
	v_cvt_pk_bf16_f32 v0, v4, v5
	v_cvt_pk_bf16_f32 v1, v6, v7
	v_cvt_pk_bf16_f32 v2, v8, v9
	v_cvt_pk_bf16_f32 v3, v10, v3
	global_store_dwordx4 v[12:13], v[0:3], off offset:256 nt
	s_cbranch_vccnz .LBB0_717
	s_andn2_b64 vcc, exec, s[0:1]
	s_cbranch_vccnz .LBB0_716
	s_barrier
	s_branch .LBB0_716
